# v51 = v49 + mod_item (adaLN GEMV, phase 0): the eight ada_w row loads of each trip issued together instead of eight dependent load/wait/FMA blocks
# speedup vs baseline: 1.0109x; 1.0109x over previous
.LBB0_147:
	v_lshl_add_u64 v[106:107], v[76:77], 0, s[68:69]
	ds_read_b128 v[4:7], v72
	ds_read_b128 v[0:3], v72 offset:16
	global_load_dwordx4 v[112:115], v[106:107], off
	v_add_co_u32_e32 v208, vcc, 0x6000, v106
	s_nop 1
	v_addc_co_u32_e32 v209, vcc, 0, v107, vcc
	global_load_dwordx4 v[180:183], v[208:209], off
	v_add_co_u32_e32 v208, vcc, 0xc000, v106
	s_nop 1
	v_addc_co_u32_e32 v209, vcc, 0, v107, vcc
	global_load_dwordx4 v[184:187], v[208:209], off
	v_add_co_u32_e32 v208, vcc, 0x12000, v106
	s_nop 1
	v_addc_co_u32_e32 v209, vcc, 0, v107, vcc
	global_load_dwordx4 v[188:191], v[208:209], off
	v_add_co_u32_e32 v208, vcc, 0x18000, v106
	s_nop 1
	v_addc_co_u32_e32 v209, vcc, 0, v107, vcc
	global_load_dwordx4 v[192:195], v[208:209], off
	v_add_co_u32_e32 v208, vcc, 0x1e000, v106
	s_nop 1
	v_addc_co_u32_e32 v209, vcc, 0, v107, vcc
	global_load_dwordx4 v[196:199], v[208:209], off
	v_add_co_u32_e32 v208, vcc, 0x24000, v106
	s_nop 1
	v_addc_co_u32_e32 v209, vcc, 0, v107, vcc
	global_load_dwordx4 v[200:203], v[208:209], off
	v_add_co_u32_e32 v208, vcc, 0x2a000, v106
	s_nop 1
	v_addc_co_u32_e32 v209, vcc, 0, v107, vcc
	global_load_dwordx4 v[204:207], v[208:209], off
	s_mov_b32 s24, 0xc000
	s_add_u32 s68, s68, 0x30000
	s_addc_u32 s69, s69, 0
	s_cmp_eq_u32 s68, 0xc0000
	s_waitcnt vmcnt(0) lgkmcnt(1)
	v_pk_fma_f32 v[108:109], v[114:115], v[4:5], v[8:9] op_sel_hi:[1,0,1]
	ds_read_b128 v[8:11], v72 offset:2048
	v_pk_fma_f32 v[104:105], v[112:113], v[4:5], v[104:105] op_sel_hi:[1,0,1]
	s_waitcnt lgkmcnt(0)
	v_pk_fma_f32 v[116:117], v[114:115], v[8:9], v[12:13] op_sel_hi:[1,0,1]
	ds_read_b128 v[12:15], v72 offset:4096
	v_pk_fma_f32 v[102:103], v[112:113], v[8:9], v[102:103] op_sel_hi:[1,0,1]
	s_waitcnt lgkmcnt(0)
	v_pk_fma_f32 v[118:119], v[114:115], v[12:13], v[16:17] op_sel_hi:[1,0,1]
	ds_read_b128 v[16:19], v72 offset:6144
	v_pk_fma_f32 v[100:101], v[112:113], v[12:13], v[100:101] op_sel_hi:[1,0,1]
	s_waitcnt lgkmcnt(0)
	v_pk_fma_f32 v[120:121], v[114:115], v[16:17], v[20:21] op_sel_hi:[1,0,1]
	ds_read_b128 v[20:23], v72 offset:8192
	v_pk_fma_f32 v[98:99], v[112:113], v[16:17], v[98:99] op_sel_hi:[1,0,1]
	s_waitcnt lgkmcnt(0)
	v_pk_fma_f32 v[122:123], v[114:115], v[20:21], v[24:25] op_sel_hi:[1,0,1]
	ds_read_b128 v[24:27], v72 offset:10240
	v_pk_fma_f32 v[96:97], v[112:113], v[20:21], v[96:97] op_sel_hi:[1,0,1]
	s_waitcnt lgkmcnt(0)
	v_pk_fma_f32 v[124:125], v[114:115], v[24:25], v[28:29] op_sel_hi:[1,0,1]
	ds_read_b128 v[28:31], v72 offset:12288
	v_pk_fma_f32 v[94:95], v[112:113], v[24:25], v[94:95] op_sel_hi:[1,0,1]
	s_waitcnt lgkmcnt(0)
	v_pk_fma_f32 v[126:127], v[114:115], v[28:29], v[32:33] op_sel_hi:[1,0,1]
	ds_read_b128 v[32:35], v72 offset:14336
	v_pk_fma_f32 v[92:93], v[112:113], v[28:29], v[92:93] op_sel_hi:[1,0,1]
	s_waitcnt lgkmcnt(0)
	v_pk_fma_f32 v[128:129], v[114:115], v[32:33], v[36:37] op_sel_hi:[1,0,1]
	ds_read_b128 v[36:39], v72 offset:16384
	v_pk_fma_f32 v[90:91], v[112:113], v[32:33], v[90:91] op_sel_hi:[1,0,1]
	s_waitcnt lgkmcnt(0)
	v_pk_fma_f32 v[130:131], v[114:115], v[36:37], v[40:41] op_sel_hi:[1,0,1]
	ds_read_b128 v[40:43], v72 offset:18432
	v_pk_fma_f32 v[88:89], v[112:113], v[36:37], v[88:89] op_sel_hi:[1,0,1]
	s_waitcnt lgkmcnt(0)
	v_pk_fma_f32 v[132:133], v[114:115], v[40:41], v[44:45] op_sel_hi:[1,0,1]
	ds_read_b128 v[44:47], v72 offset:20480
	v_pk_fma_f32 v[86:87], v[112:113], v[40:41], v[86:87] op_sel_hi:[1,0,1]
	s_waitcnt lgkmcnt(0)
	v_pk_fma_f32 v[134:135], v[114:115], v[44:45], v[48:49] op_sel_hi:[1,0,1]
	ds_read_b128 v[48:51], v72 offset:22528
	v_pk_fma_f32 v[84:85], v[112:113], v[44:45], v[84:85] op_sel_hi:[1,0,1]
	s_waitcnt lgkmcnt(0)
	v_pk_fma_f32 v[136:137], v[114:115], v[48:49], v[52:53] op_sel_hi:[1,0,1]
	ds_read_b128 v[52:55], v72 offset:24576
	v_pk_fma_f32 v[82:83], v[112:113], v[48:49], v[82:83] op_sel_hi:[1,0,1]
	s_waitcnt lgkmcnt(0)
	v_pk_fma_f32 v[146:147], v[112:113], v[52:53], v[58:59] op_sel_hi:[1,0,1]
	v_pk_fma_f32 v[148:149], v[114:115], v[52:53], v[56:57] op_sel_hi:[1,0,1]
	ds_read_b128 v[56:59], v72 offset:26624
	s_waitcnt lgkmcnt(0)
	v_pk_fma_f32 v[150:151], v[112:113], v[56:57], v[62:63] op_sel_hi:[1,0,1]
	v_pk_fma_f32 v[152:153], v[114:115], v[56:57], v[60:61] op_sel_hi:[1,0,1]
	ds_read_b128 v[60:63], v72 offset:28672
	s_waitcnt lgkmcnt(0)
	v_pk_fma_f32 v[154:155], v[112:113], v[60:61], v[66:67] op_sel_hi:[1,0,1]
	v_pk_fma_f32 v[156:157], v[114:115], v[60:61], v[64:65] op_sel_hi:[1,0,1]
	ds_read_b128 v[64:67], v72 offset:30720
	s_waitcnt lgkmcnt(0)
	v_pk_fma_f32 v[158:159], v[112:113], v[64:65], v[70:71] op_sel_hi:[1,0,1]
	v_pk_fma_f32 v[160:161], v[114:115], v[64:65], v[68:69] op_sel_hi:[1,0,1]
	ds_read_b128 v[68:71], v72 offset:32768
	s_waitcnt lgkmcnt(0)
	v_pk_fma_f32 v[114:115], v[114:115], v[68:69], v[78:79] op_sel_hi:[1,0,1]
	v_add_co_u32_e32 v78, vcc, s75, v106
	v_pk_fma_f32 v[112:113], v[112:113], v[68:69], v[80:81] op_sel_hi:[1,0,1]
	s_nop 0
	v_addc_co_u32_e32 v79, vcc, 0, v107, vcc
	s_waitcnt vmcnt(0)
	v_mov_b64_e32 v[78:79], v[180:181]
	v_mov_b64_e32 v[80:81], v[182:183]
	v_pk_fma_f32 v[104:105], v[78:79], v[4:5], v[104:105] op_sel:[0,1,0]
	v_pk_fma_f32 v[4:5], v[80:81], v[4:5], v[108:109] op_sel:[0,1,0]
	v_pk_fma_f32 v[102:103], v[78:79], v[8:9], v[102:103] op_sel:[0,1,0]
	v_pk_fma_f32 v[8:9], v[80:81], v[8:9], v[116:117] op_sel:[0,1,0]
	v_pk_fma_f32 v[100:101], v[78:79], v[12:13], v[100:101] op_sel:[0,1,0]
	v_pk_fma_f32 v[12:13], v[80:81], v[12:13], v[118:119] op_sel:[0,1,0]
	v_pk_fma_f32 v[98:99], v[78:79], v[16:17], v[98:99] op_sel:[0,1,0]
	v_pk_fma_f32 v[16:17], v[80:81], v[16:17], v[120:121] op_sel:[0,1,0]
	v_pk_fma_f32 v[96:97], v[78:79], v[20:21], v[96:97] op_sel:[0,1,0]
	v_pk_fma_f32 v[94:95], v[78:79], v[24:25], v[94:95] op_sel:[0,1,0]
	v_pk_fma_f32 v[92:93], v[78:79], v[28:29], v[92:93] op_sel:[0,1,0]
	v_pk_fma_f32 v[90:91], v[78:79], v[32:33], v[90:91] op_sel:[0,1,0]
	v_pk_fma_f32 v[88:89], v[78:79], v[36:37], v[88:89] op_sel:[0,1,0]
	v_pk_fma_f32 v[86:87], v[78:79], v[40:41], v[86:87] op_sel:[0,1,0]
	v_pk_fma_f32 v[84:85], v[78:79], v[44:45], v[84:85] op_sel:[0,1,0]
	v_pk_fma_f32 v[82:83], v[78:79], v[48:49], v[82:83] op_sel:[0,1,0]
	v_pk_fma_f32 v[108:109], v[78:79], v[52:53], v[146:147] op_sel:[0,1,0]
	v_pk_fma_f32 v[116:117], v[78:79], v[56:57], v[150:151] op_sel:[0,1,0]
	v_pk_fma_f32 v[118:119], v[78:79], v[60:61], v[154:155] op_sel:[0,1,0]
	v_pk_fma_f32 v[120:121], v[78:79], v[64:65], v[158:159] op_sel:[0,1,0]
	v_pk_fma_f32 v[112:113], v[78:79], v[68:69], v[112:113] op_sel:[0,1,0]
	v_add_co_u32_e32 v78, vcc, s24, v106
	v_pk_fma_f32 v[20:21], v[80:81], v[20:21], v[122:123] op_sel:[0,1,0]
	s_nop 0
	v_addc_co_u32_e32 v79, vcc, 0, v107, vcc
	v_pk_fma_f32 v[24:25], v[80:81], v[24:25], v[124:125] op_sel:[0,1,0]
	v_pk_fma_f32 v[28:29], v[80:81], v[28:29], v[126:127] op_sel:[0,1,0]
	v_pk_fma_f32 v[32:33], v[80:81], v[32:33], v[128:129] op_sel:[0,1,0]
	v_pk_fma_f32 v[36:37], v[80:81], v[36:37], v[130:131] op_sel:[0,1,0]
	v_pk_fma_f32 v[40:41], v[80:81], v[40:41], v[132:133] op_sel:[0,1,0]
	v_pk_fma_f32 v[44:45], v[80:81], v[44:45], v[134:135] op_sel:[0,1,0]
	v_pk_fma_f32 v[48:49], v[80:81], v[48:49], v[136:137] op_sel:[0,1,0]
	v_pk_fma_f32 v[52:53], v[80:81], v[52:53], v[148:149] op_sel:[0,1,0]
	v_pk_fma_f32 v[56:57], v[80:81], v[56:57], v[152:153] op_sel:[0,1,0]
	v_pk_fma_f32 v[60:61], v[80:81], v[60:61], v[156:157] op_sel:[0,1,0]
	v_pk_fma_f32 v[64:65], v[80:81], v[64:65], v[160:161] op_sel:[0,1,0]
	v_pk_fma_f32 v[68:69], v[80:81], v[68:69], v[114:115] op_sel:[0,1,0]
	s_mov_b32 s24, 0x12000
	s_waitcnt vmcnt(0)
	v_mov_b64_e32 v[78:79], v[184:185]
	v_mov_b64_e32 v[80:81], v[186:187]
	v_pk_fma_f32 v[122:123], v[80:81], v[14:15], v[12:13] op_sel_hi:[1,0,1]
	v_add_co_u32_e32 v12, vcc, s24, v106
	v_pk_fma_f32 v[156:157], v[78:79], v[70:71], v[112:113] op_sel_hi:[1,0,1]
	s_nop 0
	v_addc_co_u32_e32 v13, vcc, 0, v107, vcc
	v_pk_fma_f32 v[104:105], v[78:79], v[6:7], v[104:105] op_sel_hi:[1,0,1]
	v_pk_fma_f32 v[4:5], v[80:81], v[6:7], v[4:5] op_sel_hi:[1,0,1]
	v_mov_b32_e32 v6, v7
	v_pk_fma_f32 v[102:103], v[78:79], v[10:11], v[102:103] op_sel_hi:[1,0,1]
	v_pk_fma_f32 v[8:9], v[80:81], v[10:11], v[8:9] op_sel_hi:[1,0,1]
	v_pk_fma_f32 v[100:101], v[78:79], v[14:15], v[100:101] op_sel_hi:[1,0,1]
	v_pk_fma_f32 v[150:151], v[78:79], v[54:55], v[108:109] op_sel_hi:[1,0,1]
	v_pk_fma_f32 v[98:99], v[78:79], v[18:19], v[98:99] op_sel_hi:[1,0,1]
	v_pk_fma_f32 v[124:125], v[80:81], v[18:19], v[16:17] op_sel_hi:[1,0,1]
	v_pk_fma_f32 v[96:97], v[78:79], v[22:23], v[96:97] op_sel_hi:[1,0,1]
	v_pk_fma_f32 v[126:127], v[80:81], v[22:23], v[20:21] op_sel_hi:[1,0,1]
	v_pk_fma_f32 v[94:95], v[78:79], v[26:27], v[94:95] op_sel_hi:[1,0,1]
	v_pk_fma_f32 v[128:129], v[80:81], v[26:27], v[24:25] op_sel_hi:[1,0,1]
	v_pk_fma_f32 v[92:93], v[78:79], v[30:31], v[92:93] op_sel_hi:[1,0,1]
	v_pk_fma_f32 v[130:131], v[80:81], v[30:31], v[28:29] op_sel_hi:[1,0,1]
	v_pk_fma_f32 v[90:91], v[78:79], v[34:35], v[90:91] op_sel_hi:[1,0,1]
	v_pk_fma_f32 v[132:133], v[80:81], v[34:35], v[32:33] op_sel_hi:[1,0,1]
	v_pk_fma_f32 v[88:89], v[78:79], v[38:39], v[88:89] op_sel_hi:[1,0,1]
	v_pk_fma_f32 v[134:135], v[80:81], v[38:39], v[36:37] op_sel_hi:[1,0,1]
	v_pk_fma_f32 v[86:87], v[78:79], v[42:43], v[86:87] op_sel_hi:[1,0,1]
	v_pk_fma_f32 v[136:137], v[80:81], v[42:43], v[40:41] op_sel_hi:[1,0,1]
	v_pk_fma_f32 v[84:85], v[78:79], v[46:47], v[84:85] op_sel_hi:[1,0,1]
	v_pk_fma_f32 v[146:147], v[80:81], v[46:47], v[44:45] op_sel_hi:[1,0,1]
	v_pk_fma_f32 v[82:83], v[78:79], v[50:51], v[82:83] op_sel_hi:[1,0,1]
	v_pk_fma_f32 v[148:149], v[80:81], v[50:51], v[48:49] op_sel_hi:[1,0,1]
	v_pk_fma_f32 v[152:153], v[80:81], v[54:55], v[52:53] op_sel_hi:[1,0,1]
	v_pk_fma_f32 v[116:117], v[78:79], v[58:59], v[116:117] op_sel_hi:[1,0,1]
	v_pk_fma_f32 v[56:57], v[80:81], v[58:59], v[56:57] op_sel_hi:[1,0,1]
	v_pk_fma_f32 v[118:119], v[78:79], v[62:63], v[118:119] op_sel_hi:[1,0,1]
	v_pk_fma_f32 v[60:61], v[80:81], v[62:63], v[60:61] op_sel_hi:[1,0,1]
	v_pk_fma_f32 v[120:121], v[78:79], v[66:67], v[120:121] op_sel_hi:[1,0,1]
	v_pk_fma_f32 v[154:155], v[80:81], v[66:67], v[64:65] op_sel_hi:[1,0,1]
	v_pk_fma_f32 v[158:159], v[80:81], v[70:71], v[68:69] op_sel_hi:[1,0,1]
	s_mov_b32 s24, 0x18000
	s_waitcnt vmcnt(0)
	v_mov_b64_e32 v[112:113], v[188:189]
	v_mov_b64_e32 v[114:115], v[190:191]
	v_pk_fma_f32 v[162:163], v[114:115], v[6:7], v[4:5] op_sel_hi:[1,0,1]
	v_mov_b32_e32 v4, v11
	v_pk_fma_f32 v[12:13], v[112:113], v[4:5], v[102:103] op_sel_hi:[1,0,1]
	v_pk_fma_f32 v[108:109], v[114:115], v[4:5], v[8:9] op_sel_hi:[1,0,1]
	v_mov_b32_e32 v4, v15
	v_pk_fma_f32 v[160:161], v[112:113], v[6:7], v[104:105] op_sel_hi:[1,0,1]
	v_pk_fma_f32 v[16:17], v[112:113], v[4:5], v[100:101] op_sel_hi:[1,0,1]
	v_pk_fma_f32 v[104:105], v[114:115], v[4:5], v[122:123] op_sel_hi:[1,0,1]
	v_mov_b32_e32 v4, v19
	v_pk_fma_f32 v[20:21], v[112:113], v[4:5], v[98:99] op_sel_hi:[1,0,1]
	v_pk_fma_f32 v[102:103], v[114:115], v[4:5], v[124:125] op_sel_hi:[1,0,1]
	v_mov_b32_e32 v4, v23
	v_pk_fma_f32 v[24:25], v[112:113], v[4:5], v[96:97] op_sel_hi:[1,0,1]
	v_pk_fma_f32 v[100:101], v[114:115], v[4:5], v[126:127] op_sel_hi:[1,0,1]
	v_mov_b32_e32 v4, v27
	v_pk_fma_f32 v[28:29], v[112:113], v[4:5], v[94:95] op_sel_hi:[1,0,1]
	v_pk_fma_f32 v[98:99], v[114:115], v[4:5], v[128:129] op_sel_hi:[1,0,1]
	v_mov_b32_e32 v4, v31
	v_pk_fma_f32 v[32:33], v[112:113], v[4:5], v[92:93] op_sel_hi:[1,0,1]
	v_pk_fma_f32 v[96:97], v[114:115], v[4:5], v[130:131] op_sel_hi:[1,0,1]
	v_mov_b32_e32 v4, v35
	v_pk_fma_f32 v[36:37], v[112:113], v[4:5], v[90:91] op_sel_hi:[1,0,1]
	v_pk_fma_f32 v[94:95], v[114:115], v[4:5], v[132:133] op_sel_hi:[1,0,1]
	v_mov_b32_e32 v4, v39
	v_pk_fma_f32 v[40:41], v[112:113], v[4:5], v[88:89] op_sel_hi:[1,0,1]
	v_pk_fma_f32 v[92:93], v[114:115], v[4:5], v[134:135] op_sel_hi:[1,0,1]
	v_mov_b32_e32 v4, v43
	v_pk_fma_f32 v[44:45], v[112:113], v[4:5], v[86:87] op_sel_hi:[1,0,1]
	v_pk_fma_f32 v[90:91], v[114:115], v[4:5], v[136:137] op_sel_hi:[1,0,1]
	v_mov_b32_e32 v4, v47
	v_pk_fma_f32 v[48:49], v[112:113], v[4:5], v[84:85] op_sel_hi:[1,0,1]
	v_pk_fma_f32 v[88:89], v[114:115], v[4:5], v[146:147] op_sel_hi:[1,0,1]
	v_mov_b32_e32 v4, v51
	v_pk_fma_f32 v[52:53], v[112:113], v[4:5], v[82:83] op_sel_hi:[1,0,1]
	v_pk_fma_f32 v[86:87], v[114:115], v[4:5], v[148:149] op_sel_hi:[1,0,1]
	v_mov_b32_e32 v4, v55
	v_pk_fma_f32 v[82:83], v[112:113], v[4:5], v[150:151] op_sel_hi:[1,0,1]
	v_pk_fma_f32 v[84:85], v[114:115], v[4:5], v[152:153] op_sel_hi:[1,0,1]
	v_mov_b32_e32 v4, v59
	v_pk_fma_f32 v[78:79], v[112:113], v[4:5], v[116:117] op_sel_hi:[1,0,1]
	v_pk_fma_f32 v[80:81], v[114:115], v[4:5], v[56:57] op_sel_hi:[1,0,1]
	v_mov_b32_e32 v4, v63
	v_pk_fma_f32 v[64:65], v[112:113], v[4:5], v[118:119] op_sel_hi:[1,0,1]
	v_pk_fma_f32 v[68:69], v[114:115], v[4:5], v[60:61] op_sel_hi:[1,0,1]
	v_mov_b32_e32 v4, v67
	v_pk_fma_f32 v[60:61], v[112:113], v[4:5], v[120:121] op_sel_hi:[1,0,1]
	v_pk_fma_f32 v[62:63], v[114:115], v[4:5], v[154:155] op_sel_hi:[1,0,1]
	v_mov_b32_e32 v4, v71
	v_pk_fma_f32 v[56:57], v[112:113], v[4:5], v[156:157] op_sel_hi:[1,0,1]
	v_pk_fma_f32 v[58:59], v[114:115], v[4:5], v[158:159] op_sel_hi:[1,0,1]
	v_add_co_u32_e32 v4, vcc, s24, v106
	ds_read_b128 v[8:11], v72 offset:2064
	ds_read_b128 v[120:123], v72 offset:32784
	v_addc_co_u32_e32 v5, vcc, 0, v107, vcc
	ds_read_b128 v[112:115], v72 offset:26640
	ds_read_b128 v[116:119], v72 offset:30736
	s_mov_b32 s24, 0x1e000
	s_waitcnt vmcnt(0) lgkmcnt(3)
	v_mov_b64_e32 v[4:5], v[192:193]
	v_mov_b64_e32 v[6:7], v[194:195]
	v_pk_fma_f32 v[124:125], v[4:5], v[8:9], v[12:13] op_sel_hi:[1,0,1]
	ds_read_b128 v[12:15], v72 offset:4112
	s_waitcnt lgkmcnt(2)
	v_pk_fma_f32 v[154:155], v[4:5], v[112:113], v[78:79] op_sel_hi:[1,0,1]
	v_pk_fma_f32 v[156:157], v[6:7], v[112:113], v[80:81] op_sel_hi:[1,0,1]
	ds_read_b128 v[78:81], v72 offset:28688
	v_pk_fma_f32 v[66:67], v[4:5], v[0:1], v[160:161] op_sel_hi:[1,0,1]
	s_waitcnt lgkmcnt(1)
	v_pk_fma_f32 v[126:127], v[4:5], v[12:13], v[16:17] op_sel_hi:[1,0,1]
	ds_read_b128 v[16:19], v72 offset:6160
	v_pk_fma_f32 v[60:61], v[4:5], v[116:117], v[60:61] op_sel_hi:[1,0,1]
	s_waitcnt lgkmcnt(1)
	v_pk_fma_f32 v[64:65], v[4:5], v[78:79], v[64:65] op_sel_hi:[1,0,1]
	v_pk_fma_f32 v[56:57], v[4:5], v[120:121], v[56:57] op_sel_hi:[1,0,1]
	v_pk_fma_f32 v[70:71], v[6:7], v[0:1], v[162:163] op_sel_hi:[1,0,1]
	s_waitcnt lgkmcnt(0)
	v_pk_fma_f32 v[128:129], v[4:5], v[16:17], v[20:21] op_sel_hi:[1,0,1]
	ds_read_b128 v[20:23], v72 offset:8208
	v_pk_fma_f32 v[108:109], v[6:7], v[8:9], v[108:109] op_sel_hi:[1,0,1]
	v_pk_fma_f32 v[104:105], v[6:7], v[12:13], v[104:105] op_sel_hi:[1,0,1]
	v_pk_fma_f32 v[102:103], v[6:7], v[16:17], v[102:103] op_sel_hi:[1,0,1]
	v_pk_fma_f32 v[68:69], v[6:7], v[78:79], v[68:69] op_sel_hi:[1,0,1]
	s_waitcnt lgkmcnt(0)
	v_pk_fma_f32 v[130:131], v[4:5], v[20:21], v[24:25] op_sel_hi:[1,0,1]
	ds_read_b128 v[24:27], v72 offset:10256
	v_pk_fma_f32 v[100:101], v[6:7], v[20:21], v[100:101] op_sel_hi:[1,0,1]
	v_pk_fma_f32 v[62:63], v[6:7], v[116:117], v[62:63] op_sel_hi:[1,0,1]
	v_pk_fma_f32 v[58:59], v[6:7], v[120:121], v[58:59] op_sel_hi:[1,0,1]
	s_waitcnt lgkmcnt(0)
	v_pk_fma_f32 v[132:133], v[4:5], v[24:25], v[28:29] op_sel_hi:[1,0,1]
	ds_read_b128 v[28:31], v72 offset:12304
	v_pk_fma_f32 v[98:99], v[6:7], v[24:25], v[98:99] op_sel_hi:[1,0,1]
	s_waitcnt lgkmcnt(0)
	v_pk_fma_f32 v[134:135], v[4:5], v[28:29], v[32:33] op_sel_hi:[1,0,1]
	ds_read_b128 v[32:35], v72 offset:14352
	v_pk_fma_f32 v[96:97], v[6:7], v[28:29], v[96:97] op_sel_hi:[1,0,1]
	s_waitcnt lgkmcnt(0)
	v_pk_fma_f32 v[136:137], v[4:5], v[32:33], v[36:37] op_sel_hi:[1,0,1]
	ds_read_b128 v[36:39], v72 offset:16400
	v_pk_fma_f32 v[94:95], v[6:7], v[32:33], v[94:95] op_sel_hi:[1,0,1]
	s_waitcnt lgkmcnt(0)
	v_pk_fma_f32 v[146:147], v[4:5], v[36:37], v[40:41] op_sel_hi:[1,0,1]
	ds_read_b128 v[40:43], v72 offset:18448
	v_pk_fma_f32 v[92:93], v[6:7], v[36:37], v[92:93] op_sel_hi:[1,0,1]
	s_waitcnt lgkmcnt(0)
	v_pk_fma_f32 v[148:149], v[4:5], v[40:41], v[44:45] op_sel_hi:[1,0,1]
	ds_read_b128 v[44:47], v72 offset:20496
	v_pk_fma_f32 v[90:91], v[6:7], v[40:41], v[90:91] op_sel_hi:[1,0,1]
	s_waitcnt lgkmcnt(0)
	v_pk_fma_f32 v[150:151], v[4:5], v[44:45], v[48:49] op_sel_hi:[1,0,1]
	ds_read_b128 v[48:51], v72 offset:22544
	v_pk_fma_f32 v[88:89], v[6:7], v[44:45], v[88:89] op_sel_hi:[1,0,1]
	s_waitcnt lgkmcnt(0)
	v_pk_fma_f32 v[152:153], v[4:5], v[48:49], v[52:53] op_sel_hi:[1,0,1]
	ds_read_b128 v[52:55], v72 offset:24592
	v_pk_fma_f32 v[86:87], v[6:7], v[48:49], v[86:87] op_sel_hi:[1,0,1]
	v_add_u32_e32 v72, 32, v72
	s_waitcnt lgkmcnt(0)
	v_pk_fma_f32 v[82:83], v[4:5], v[52:53], v[82:83] op_sel_hi:[1,0,1]
	v_add_co_u32_e32 v4, vcc, s24, v106
	v_pk_fma_f32 v[84:85], v[6:7], v[52:53], v[84:85] op_sel_hi:[1,0,1]
	s_nop 0
	v_addc_co_u32_e32 v5, vcc, 0, v107, vcc
	s_mov_b32 s24, 0x24000
	s_waitcnt vmcnt(0)
	v_mov_b64_e32 v[4:5], v[196:197]
	v_mov_b64_e32 v[6:7], v[198:199]
	v_pk_fma_f32 v[66:67], v[4:5], v[0:1], v[66:67] op_sel:[0,1,0]
	v_pk_fma_f32 v[0:1], v[6:7], v[0:1], v[70:71] op_sel:[0,1,0]
	v_pk_fma_f32 v[70:71], v[4:5], v[8:9], v[124:125] op_sel:[0,1,0]
	v_pk_fma_f32 v[8:9], v[6:7], v[8:9], v[108:109] op_sel:[0,1,0]
	v_pk_fma_f32 v[108:109], v[4:5], v[12:13], v[126:127] op_sel:[0,1,0]
	v_pk_fma_f32 v[12:13], v[6:7], v[12:13], v[104:105] op_sel:[0,1,0]
	v_pk_fma_f32 v[104:105], v[4:5], v[16:17], v[128:129] op_sel:[0,1,0]
	v_pk_fma_f32 v[16:17], v[6:7], v[16:17], v[102:103] op_sel:[0,1,0]
	v_pk_fma_f32 v[102:103], v[4:5], v[20:21], v[130:131] op_sel:[0,1,0]
	v_pk_fma_f32 v[20:21], v[6:7], v[20:21], v[100:101] op_sel:[0,1,0]
	v_pk_fma_f32 v[100:101], v[4:5], v[24:25], v[132:133] op_sel:[0,1,0]
	v_pk_fma_f32 v[24:25], v[6:7], v[24:25], v[98:99] op_sel:[0,1,0]
	v_pk_fma_f32 v[98:99], v[4:5], v[28:29], v[134:135] op_sel:[0,1,0]
	v_pk_fma_f32 v[28:29], v[6:7], v[28:29], v[96:97] op_sel:[0,1,0]
	v_pk_fma_f32 v[96:97], v[4:5], v[32:33], v[136:137] op_sel:[0,1,0]
	v_pk_fma_f32 v[32:33], v[6:7], v[32:33], v[94:95] op_sel:[0,1,0]
	v_pk_fma_f32 v[94:95], v[4:5], v[36:37], v[146:147] op_sel:[0,1,0]
	v_pk_fma_f32 v[36:37], v[6:7], v[36:37], v[92:93] op_sel:[0,1,0]
	v_pk_fma_f32 v[92:93], v[4:5], v[40:41], v[148:149] op_sel:[0,1,0]
	v_pk_fma_f32 v[40:41], v[6:7], v[40:41], v[90:91] op_sel:[0,1,0]
	v_pk_fma_f32 v[90:91], v[4:5], v[44:45], v[150:151] op_sel:[0,1,0]
	v_pk_fma_f32 v[44:45], v[6:7], v[44:45], v[88:89] op_sel:[0,1,0]
	v_pk_fma_f32 v[88:89], v[4:5], v[48:49], v[152:153] op_sel:[0,1,0]
	v_pk_fma_f32 v[82:83], v[4:5], v[52:53], v[82:83] op_sel:[0,1,0]
	v_pk_fma_f32 v[52:53], v[6:7], v[52:53], v[84:85] op_sel:[0,1,0]
	v_pk_fma_f32 v[84:85], v[4:5], v[112:113], v[154:155] op_sel:[0,1,0]
	v_pk_fma_f32 v[64:65], v[4:5], v[78:79], v[64:65] op_sel:[0,1,0]
	v_pk_fma_f32 v[60:61], v[4:5], v[116:117], v[60:61] op_sel:[0,1,0]
	v_pk_fma_f32 v[56:57], v[4:5], v[120:121], v[56:57] op_sel:[0,1,0]
	v_add_co_u32_e32 v4, vcc, s24, v106
	v_pk_fma_f32 v[48:49], v[6:7], v[48:49], v[86:87] op_sel:[0,1,0]
	s_nop 0
	v_addc_co_u32_e32 v5, vcc, 0, v107, vcc
	v_pk_fma_f32 v[86:87], v[6:7], v[112:113], v[156:157] op_sel:[0,1,0]
	v_pk_fma_f32 v[68:69], v[6:7], v[78:79], v[68:69] op_sel:[0,1,0]
	v_pk_fma_f32 v[62:63], v[6:7], v[116:117], v[62:63] op_sel:[0,1,0]
	v_pk_fma_f32 v[58:59], v[6:7], v[120:121], v[58:59] op_sel:[0,1,0]
	s_mov_b32 s24, 0x2a000
	s_waitcnt vmcnt(0)
	v_mov_b64_e32 v[4:5], v[200:201]
	v_mov_b64_e32 v[6:7], v[202:203]
	v_pk_fma_f32 v[66:67], v[4:5], v[2:3], v[66:67] op_sel_hi:[1,0,1]
	v_pk_fma_f32 v[70:71], v[4:5], v[10:11], v[70:71] op_sel_hi:[1,0,1]
	v_pk_fma_f32 v[108:109], v[4:5], v[14:15], v[108:109] op_sel_hi:[1,0,1]
	v_pk_fma_f32 v[116:117], v[4:5], v[18:19], v[104:105] op_sel_hi:[1,0,1]
	v_pk_fma_f32 v[124:125], v[4:5], v[22:23], v[102:103] op_sel_hi:[1,0,1]
	v_pk_fma_f32 v[128:129], v[4:5], v[26:27], v[100:101] op_sel_hi:[1,0,1]
	v_pk_fma_f32 v[132:133], v[4:5], v[30:31], v[98:99] op_sel_hi:[1,0,1]
	v_pk_fma_f32 v[136:137], v[4:5], v[34:35], v[96:97] op_sel_hi:[1,0,1]
	v_pk_fma_f32 v[148:149], v[4:5], v[38:39], v[94:95] op_sel_hi:[1,0,1]
	v_pk_fma_f32 v[152:153], v[4:5], v[42:43], v[92:93] op_sel_hi:[1,0,1]
	v_pk_fma_f32 v[156:157], v[4:5], v[46:47], v[90:91] op_sel_hi:[1,0,1]
	v_pk_fma_f32 v[160:161], v[4:5], v[50:51], v[88:89] op_sel_hi:[1,0,1]
	v_pk_fma_f32 v[164:165], v[4:5], v[54:55], v[82:83] op_sel_hi:[1,0,1]
	v_pk_fma_f32 v[168:169], v[4:5], v[114:115], v[84:85] op_sel_hi:[1,0,1]
	v_pk_fma_f32 v[64:65], v[4:5], v[80:81], v[64:65] op_sel_hi:[1,0,1]
	v_pk_fma_f32 v[172:173], v[4:5], v[118:119], v[60:61] op_sel_hi:[1,0,1]
	v_pk_fma_f32 v[176:177], v[4:5], v[122:123], v[56:57] op_sel_hi:[1,0,1]
	v_add_co_u32_e32 v4, vcc, s24, v106
	v_pk_fma_f32 v[0:1], v[6:7], v[2:3], v[0:1] op_sel_hi:[1,0,1]
	s_nop 0
	v_addc_co_u32_e32 v5, vcc, 0, v107, vcc
	v_pk_fma_f32 v[78:79], v[6:7], v[10:11], v[8:9] op_sel_hi:[1,0,1]
	v_pk_fma_f32 v[112:113], v[6:7], v[14:15], v[12:13] op_sel_hi:[1,0,1]
	v_pk_fma_f32 v[120:121], v[6:7], v[18:19], v[16:17] op_sel_hi:[1,0,1]
	v_pk_fma_f32 v[126:127], v[6:7], v[22:23], v[20:21] op_sel_hi:[1,0,1]
	v_pk_fma_f32 v[130:131], v[6:7], v[26:27], v[24:25] op_sel_hi:[1,0,1]
	v_pk_fma_f32 v[134:135], v[6:7], v[30:31], v[28:29] op_sel_hi:[1,0,1]
	v_pk_fma_f32 v[146:147], v[6:7], v[34:35], v[32:33] op_sel_hi:[1,0,1]
	v_pk_fma_f32 v[150:151], v[6:7], v[38:39], v[36:37] op_sel_hi:[1,0,1]
	v_pk_fma_f32 v[154:155], v[6:7], v[42:43], v[40:41] op_sel_hi:[1,0,1]
	v_pk_fma_f32 v[158:159], v[6:7], v[46:47], v[44:45] op_sel_hi:[1,0,1]
	v_pk_fma_f32 v[162:163], v[6:7], v[50:51], v[48:49] op_sel_hi:[1,0,1]
	v_pk_fma_f32 v[166:167], v[6:7], v[54:55], v[52:53] op_sel_hi:[1,0,1]
	v_pk_fma_f32 v[170:171], v[6:7], v[114:115], v[86:87] op_sel_hi:[1,0,1]
	v_pk_fma_f32 v[68:69], v[6:7], v[80:81], v[68:69] op_sel_hi:[1,0,1]
	v_pk_fma_f32 v[174:175], v[6:7], v[118:119], v[62:63] op_sel_hi:[1,0,1]
	v_pk_fma_f32 v[178:179], v[6:7], v[122:123], v[58:59] op_sel_hi:[1,0,1]
	v_mov_b32_e32 v2, v3
	s_waitcnt vmcnt(0)
	v_mov_b64_e32 v[4:5], v[204:205]
	v_mov_b64_e32 v[6:7], v[206:207]
	v_pk_fma_f32 v[8:9], v[6:7], v[2:3], v[0:1] op_sel_hi:[1,0,1]
	v_mov_b32_e32 v0, v11
	v_pk_fma_f32 v[102:103], v[4:5], v[0:1], v[70:71] op_sel_hi:[1,0,1]
	v_pk_fma_f32 v[12:13], v[6:7], v[0:1], v[78:79] op_sel_hi:[1,0,1]
	v_mov_b32_e32 v0, v15
	v_pk_fma_f32 v[100:101], v[4:5], v[0:1], v[108:109] op_sel_hi:[1,0,1]
	v_pk_fma_f32 v[16:17], v[6:7], v[0:1], v[112:113] op_sel_hi:[1,0,1]
	v_mov_b32_e32 v0, v19
	v_pk_fma_f32 v[98:99], v[4:5], v[0:1], v[116:117] op_sel_hi:[1,0,1]
	v_pk_fma_f32 v[20:21], v[6:7], v[0:1], v[120:121] op_sel_hi:[1,0,1]
	v_mov_b32_e32 v0, v23
	v_pk_fma_f32 v[96:97], v[4:5], v[0:1], v[124:125] op_sel_hi:[1,0,1]
	v_pk_fma_f32 v[24:25], v[6:7], v[0:1], v[126:127] op_sel_hi:[1,0,1]
	v_mov_b32_e32 v0, v27
	v_pk_fma_f32 v[94:95], v[4:5], v[0:1], v[128:129] op_sel_hi:[1,0,1]
	v_pk_fma_f32 v[28:29], v[6:7], v[0:1], v[130:131] op_sel_hi:[1,0,1]
	v_mov_b32_e32 v0, v31
	v_pk_fma_f32 v[92:93], v[4:5], v[0:1], v[132:133] op_sel_hi:[1,0,1]
	v_pk_fma_f32 v[32:33], v[6:7], v[0:1], v[134:135] op_sel_hi:[1,0,1]
	v_mov_b32_e32 v0, v35
	v_pk_fma_f32 v[90:91], v[4:5], v[0:1], v[136:137] op_sel_hi:[1,0,1]
	v_pk_fma_f32 v[36:37], v[6:7], v[0:1], v[146:147] op_sel_hi:[1,0,1]
	v_mov_b32_e32 v0, v39
	v_pk_fma_f32 v[88:89], v[4:5], v[0:1], v[148:149] op_sel_hi:[1,0,1]
	v_pk_fma_f32 v[40:41], v[6:7], v[0:1], v[150:151] op_sel_hi:[1,0,1]
	v_mov_b32_e32 v0, v43
	v_pk_fma_f32 v[86:87], v[4:5], v[0:1], v[152:153] op_sel_hi:[1,0,1]
	v_pk_fma_f32 v[44:45], v[6:7], v[0:1], v[154:155] op_sel_hi:[1,0,1]
	v_mov_b32_e32 v0, v47
	v_pk_fma_f32 v[84:85], v[4:5], v[0:1], v[156:157] op_sel_hi:[1,0,1]
	v_pk_fma_f32 v[48:49], v[6:7], v[0:1], v[158:159] op_sel_hi:[1,0,1]
	v_mov_b32_e32 v0, v51
	v_pk_fma_f32 v[82:83], v[4:5], v[0:1], v[160:161] op_sel_hi:[1,0,1]
	v_pk_fma_f32 v[52:53], v[6:7], v[0:1], v[162:163] op_sel_hi:[1,0,1]
	v_mov_b32_e32 v0, v55
	v_pk_fma_f32 v[58:59], v[4:5], v[0:1], v[164:165] op_sel_hi:[1,0,1]
	v_pk_fma_f32 v[56:57], v[6:7], v[0:1], v[166:167] op_sel_hi:[1,0,1]
	v_mov_b32_e32 v0, v115
	v_pk_fma_f32 v[62:63], v[4:5], v[0:1], v[168:169] op_sel_hi:[1,0,1]
	v_pk_fma_f32 v[60:61], v[6:7], v[0:1], v[170:171] op_sel_hi:[1,0,1]
	v_mov_b32_e32 v0, v81
	v_pk_fma_f32 v[104:105], v[4:5], v[2:3], v[66:67] op_sel_hi:[1,0,1]
	v_pk_fma_f32 v[66:67], v[4:5], v[0:1], v[64:65] op_sel_hi:[1,0,1]
	v_pk_fma_f32 v[64:65], v[6:7], v[0:1], v[68:69] op_sel_hi:[1,0,1]
	v_mov_b32_e32 v0, v119
	v_pk_fma_f32 v[70:71], v[4:5], v[0:1], v[172:173] op_sel_hi:[1,0,1]
	v_pk_fma_f32 v[68:69], v[6:7], v[0:1], v[174:175] op_sel_hi:[1,0,1]
	v_mov_b32_e32 v0, v123
	v_pk_fma_f32 v[80:81], v[4:5], v[0:1], v[176:177] op_sel_hi:[1,0,1]
	v_pk_fma_f32 v[78:79], v[6:7], v[0:1], v[178:179] op_sel_hi:[1,0,1]
	s_cbranch_scc0 .LBB0_147
	s_movk_i32 s76, 0x200
	s_mov_b64 s[68:69], 0
	s_and_b64 vcc, exec, s[6:7]
	s_cbranch_vccz .LBB0_139
	v_and_b32_e32 v1, 64, v138
	v_xor_b32_e32 v0, 16, v138
	v_add_u32_e32 v2, 64, v1
	v_cmp_lt_i32_e32 vcc, v0, v2
	v_xor_b32_e32 v3, 32, v138
	v_and_b32_e32 v72, 48, v139
	v_cndmask_b32_e32 v0, v138, v0, vcc
	v_lshlrev_b32_e32 v137, 2, v0
	ds_bpermute_b32 v4, v137, v8
	ds_bpermute_b32 v5, v137, v9
	ds_bpermute_b32 v0, v137, v104
	ds_bpermute_b32 v1, v137, v105
	ds_bpermute_b32 v18, v137, v100
	ds_bpermute_b32 v19, v137, v101
	s_waitcnt lgkmcnt(4)
	v_pk_add_f32 v[4:5], v[8:9], v[4:5]
	ds_bpermute_b32 v8, v137, v102
	ds_bpermute_b32 v9, v137, v103
	ds_bpermute_b32 v30, v137, v98
	ds_bpermute_b32 v31, v137, v99
	ds_bpermute_b32 v42, v137, v96
	ds_bpermute_b32 v43, v137, v97
	ds_bpermute_b32 v54, v137, v94
	ds_bpermute_b32 v55, v137, v95
	s_waitcnt lgkmcnt(10)
	v_pk_add_f32 v[0:1], v[104:105], v[0:1]
	ds_bpermute_b32 v14, v137, v12
	ds_bpermute_b32 v15, v137, v13
	s_waitcnt lgkmcnt(8)
	v_pk_add_f32 v[8:9], v[102:103], v[8:9]
	ds_bpermute_b32 v26, v137, v16
	ds_bpermute_b32 v27, v137, v17
	v_pk_add_f32 v[18:19], v[100:101], v[18:19]
	ds_bpermute_b32 v38, v137, v20
	ds_bpermute_b32 v39, v137, v21
	s_waitcnt lgkmcnt(10)
	v_pk_add_f32 v[30:31], v[98:99], v[30:31]
	ds_bpermute_b32 v50, v137, v24
	ds_bpermute_b32 v51, v137, v25
	s_waitcnt lgkmcnt(10)
	v_pk_add_f32 v[42:43], v[96:97], v[42:43]
	ds_bpermute_b32 v76, v137, v28
	ds_bpermute_b32 v77, v137, v29
	s_waitcnt lgkmcnt(10)
	v_pk_add_f32 v[54:55], v[94:95], v[54:55]
	ds_bpermute_b32 v94, v137, v92
	ds_bpermute_b32 v95, v137, v93
	ds_bpermute_b32 v96, v137, v32
	ds_bpermute_b32 v97, v137, v33
	ds_bpermute_b32 v98, v137, v90
	ds_bpermute_b32 v99, v137, v91
	ds_bpermute_b32 v100, v137, v36
	ds_bpermute_b32 v101, v137, v37
	ds_bpermute_b32 v102, v137, v88
	ds_bpermute_b32 v103, v137, v89
	ds_bpermute_b32 v104, v137, v40
	ds_bpermute_b32 v105, v137, v41
	ds_bpermute_b32 v106, v137, v86
	ds_bpermute_b32 v107, v137, v87
	ds_bpermute_b32 v108, v137, v44
	ds_bpermute_b32 v109, v137, v45
	ds_bpermute_b32 v110, v137, v84
	ds_bpermute_b32 v111, v137, v85
	ds_bpermute_b32 v112, v137, v48
	ds_bpermute_b32 v113, v137, v49
	ds_bpermute_b32 v114, v137, v82
	ds_bpermute_b32 v115, v137, v83
	ds_bpermute_b32 v116, v137, v52
	ds_bpermute_b32 v117, v137, v53
	ds_bpermute_b32 v118, v137, v58
	ds_bpermute_b32 v119, v137, v59
	ds_bpermute_b32 v120, v137, v56
	ds_bpermute_b32 v121, v137, v57
	ds_bpermute_b32 v122, v137, v62
	ds_bpermute_b32 v123, v137, v63
	ds_bpermute_b32 v124, v137, v60
	ds_bpermute_b32 v125, v137, v61
	ds_bpermute_b32 v126, v137, v66
	ds_bpermute_b32 v127, v137, v67
	ds_bpermute_b32 v128, v137, v64
	ds_bpermute_b32 v129, v137, v65
	ds_bpermute_b32 v130, v137, v70
	ds_bpermute_b32 v131, v137, v71
	ds_bpermute_b32 v132, v137, v68
	ds_bpermute_b32 v133, v137, v69
	ds_bpermute_b32 v134, v137, v80
	ds_bpermute_b32 v135, v137, v81
	ds_bpermute_b32 v136, v137, v78
	ds_bpermute_b32 v137, v137, v79
	v_cmp_lt_i32_e32 vcc, v3, v2
	s_waitcnt lgkmcnt(14)
	v_pk_add_f32 v[12:13], v[12:13], v[14:15]
	v_pk_add_f32 v[16:17], v[16:17], v[26:27]
	v_cndmask_b32_e32 v2, v138, v3, vcc
	v_lshlrev_b32_e32 v146, 2, v2
	v_pk_add_f32 v[20:21], v[20:21], v[38:39]
	v_pk_add_f32 v[24:25], v[24:25], v[50:51]
	v_pk_add_f32 v[28:29], v[28:29], v[76:77]
	v_pk_add_f32 v[92:93], v[92:93], v[94:95]
	v_pk_add_f32 v[32:33], v[32:33], v[96:97]
	v_pk_add_f32 v[90:91], v[90:91], v[98:99]
	v_pk_add_f32 v[36:37], v[36:37], v[100:101]
	v_pk_add_f32 v[88:89], v[88:89], v[102:103]
	v_pk_add_f32 v[40:41], v[40:41], v[104:105]
	v_pk_add_f32 v[86:87], v[86:87], v[106:107]
	v_pk_add_f32 v[44:45], v[44:45], v[108:109]
	v_pk_add_f32 v[84:85], v[84:85], v[110:111]
	v_pk_add_f32 v[48:49], v[48:49], v[112:113]
	v_pk_add_f32 v[82:83], v[82:83], v[114:115]
	v_pk_add_f32 v[52:53], v[52:53], v[116:117]
	v_pk_add_f32 v[58:59], v[58:59], v[118:119]
	v_pk_add_f32 v[56:57], v[56:57], v[120:121]
	v_pk_add_f32 v[62:63], v[62:63], v[122:123]
	s_waitcnt lgkmcnt(12)
	v_pk_add_f32 v[60:61], v[60:61], v[124:125]
	s_waitcnt lgkmcnt(10)
	v_pk_add_f32 v[66:67], v[66:67], v[126:127]
	s_waitcnt lgkmcnt(8)
	v_pk_add_f32 v[64:65], v[64:65], v[128:129]
	s_waitcnt lgkmcnt(6)
	v_pk_add_f32 v[70:71], v[70:71], v[130:131]
	s_waitcnt lgkmcnt(4)
	v_pk_add_f32 v[68:69], v[68:69], v[132:133]
	s_waitcnt lgkmcnt(2)
	v_pk_add_f32 v[80:81], v[80:81], v[134:135]
	s_waitcnt lgkmcnt(0)
	v_pk_add_f32 v[78:79], v[78:79], v[136:137]
	ds_bpermute_b32 v2, v146, v0
	ds_bpermute_b32 v3, v146, v1
	ds_bpermute_b32 v6, v146, v4
	ds_bpermute_b32 v7, v146, v5
	ds_bpermute_b32 v10, v146, v8
	ds_bpermute_b32 v11, v146, v9
	ds_bpermute_b32 v14, v146, v12
	ds_bpermute_b32 v15, v146, v13
	ds_bpermute_b32 v22, v146, v18
	ds_bpermute_b32 v23, v146, v19
	ds_bpermute_b32 v26, v146, v16
	ds_bpermute_b32 v27, v146, v17
	ds_bpermute_b32 v34, v146, v30
	ds_bpermute_b32 v35, v146, v31
	ds_bpermute_b32 v38, v146, v20
	ds_bpermute_b32 v39, v146, v21
	ds_bpermute_b32 v46, v146, v42
	ds_bpermute_b32 v47, v146, v43
	ds_bpermute_b32 v50, v146, v24
	ds_bpermute_b32 v51, v146, v25
	ds_bpermute_b32 v74, v146, v54
	ds_bpermute_b32 v75, v146, v55
	ds_bpermute_b32 v76, v146, v28
	ds_bpermute_b32 v77, v146, v29
	ds_bpermute_b32 v94, v146, v92
	ds_bpermute_b32 v95, v146, v93
	ds_bpermute_b32 v96, v146, v32
	ds_bpermute_b32 v97, v146, v33
	ds_bpermute_b32 v98, v146, v90
	ds_bpermute_b32 v99, v146, v91
	ds_bpermute_b32 v100, v146, v36
	ds_bpermute_b32 v101, v146, v37
	ds_bpermute_b32 v102, v146, v88
	ds_bpermute_b32 v103, v146, v89
	ds_bpermute_b32 v104, v146, v40
	ds_bpermute_b32 v105, v146, v41
	ds_bpermute_b32 v106, v146, v86
	ds_bpermute_b32 v107, v146, v87
	ds_bpermute_b32 v108, v146, v44
	ds_bpermute_b32 v109, v146, v45
	ds_bpermute_b32 v110, v146, v84
	ds_bpermute_b32 v111, v146, v85
	ds_bpermute_b32 v112, v146, v48
	ds_bpermute_b32 v113, v146, v49
	ds_bpermute_b32 v114, v146, v82
	ds_bpermute_b32 v115, v146, v83
	ds_bpermute_b32 v116, v146, v52
	ds_bpermute_b32 v117, v146, v53
	ds_bpermute_b32 v118, v146, v58
	ds_bpermute_b32 v119, v146, v59
	ds_bpermute_b32 v120, v146, v56
	ds_bpermute_b32 v121, v146, v57
	ds_bpermute_b32 v122, v146, v62
	ds_bpermute_b32 v123, v146, v63
	ds_bpermute_b32 v124, v146, v60
	ds_bpermute_b32 v125, v146, v61
	ds_bpermute_b32 v126, v146, v66
	ds_bpermute_b32 v127, v146, v67
	ds_bpermute_b32 v128, v146, v64
	ds_bpermute_b32 v129, v146, v65
	ds_bpermute_b32 v130, v146, v70
	ds_bpermute_b32 v131, v146, v71
	ds_bpermute_b32 v132, v146, v68
	ds_bpermute_b32 v133, v146, v69
	ds_bpermute_b32 v134, v146, v80
	ds_bpermute_b32 v135, v146, v81
	ds_bpermute_b32 v136, v146, v78
	ds_bpermute_b32 v137, v146, v79
	v_cmp_eq_u32_e32 vcc, 0, v72
	s_waitcnt lgkmcnt(0)
	s_barrier
	s_and_saveexec_b64 s[4:5], vcc
	s_cbranch_execz .LBB0_151
	v_lshrrev_b32_e32 v72, 6, v139
	s_movk_i32 s6, 0x1100
	v_mul_lo_u32 v72, v72, s6
	v_lshl_or_b32 v72, v141, 2, v72
	v_pk_add_f32 v[0:1], v[0:1], v[2:3]
	v_pk_add_f32 v[2:3], v[4:5], v[6:7]
	ds_write_b128 v72, v[0:3] offset:34816
	v_pk_add_f32 v[0:1], v[8:9], v[10:11]
	v_pk_add_f32 v[2:3], v[12:13], v[14:15]
	ds_write_b128 v72, v[0:3] offset:35072
	v_pk_add_f32 v[0:1], v[18:19], v[22:23]
	v_pk_add_f32 v[2:3], v[16:17], v[26:27]
	ds_write_b128 v72, v[0:3] offset:35328
	v_pk_add_f32 v[0:1], v[30:31], v[34:35]
	v_pk_add_f32 v[2:3], v[20:21], v[38:39]
	ds_write_b128 v72, v[0:3] offset:35584
	v_pk_add_f32 v[0:1], v[42:43], v[46:47]
	v_pk_add_f32 v[2:3], v[24:25], v[50:51]
	ds_write_b128 v72, v[0:3] offset:35840
	v_pk_add_f32 v[0:1], v[54:55], v[74:75]
	v_pk_add_f32 v[2:3], v[28:29], v[76:77]
	ds_write_b128 v72, v[0:3] offset:36096
	v_pk_add_f32 v[0:1], v[92:93], v[94:95]
	v_pk_add_f32 v[2:3], v[32:33], v[96:97]
	ds_write_b128 v72, v[0:3] offset:36352
	v_pk_add_f32 v[0:1], v[90:91], v[98:99]
	v_pk_add_f32 v[2:3], v[36:37], v[100:101]
	ds_write_b128 v72, v[0:3] offset:36608
	v_pk_add_f32 v[0:1], v[88:89], v[102:103]
	v_pk_add_f32 v[2:3], v[40:41], v[104:105]
	ds_write_b128 v72, v[0:3] offset:36864
	v_pk_add_f32 v[0:1], v[86:87], v[106:107]
	v_pk_add_f32 v[2:3], v[44:45], v[108:109]
	ds_write_b128 v72, v[0:3] offset:37120
	v_pk_add_f32 v[0:1], v[84:85], v[110:111]
	v_pk_add_f32 v[2:3], v[48:49], v[112:113]
	ds_write_b128 v72, v[0:3] offset:37376
	v_pk_add_f32 v[0:1], v[82:83], v[114:115]
	v_pk_add_f32 v[2:3], v[52:53], v[116:117]
	ds_write_b128 v72, v[0:3] offset:37632
	v_pk_add_f32 v[0:1], v[58:59], v[118:119]
	v_pk_add_f32 v[2:3], v[56:57], v[120:121]
	ds_write_b128 v72, v[0:3] offset:37888
	v_pk_add_f32 v[0:1], v[62:63], v[122:123]
	v_pk_add_f32 v[2:3], v[60:61], v[124:125]
	ds_write_b128 v72, v[0:3] offset:38144
	v_pk_add_f32 v[0:1], v[66:67], v[126:127]
	v_pk_add_f32 v[2:3], v[64:65], v[128:129]
	ds_write_b128 v72, v[0:3] offset:38400
	v_pk_add_f32 v[0:1], v[70:71], v[130:131]
	v_pk_add_f32 v[2:3], v[68:69], v[132:133]
	ds_write_b128 v72, v[0:3] offset:38656
	v_pk_add_f32 v[0:1], v[80:81], v[134:135]
	v_pk_add_f32 v[2:3], v[78:79], v[136:137]
	ds_write_b128 v72, v[0:3] offset:38912
